# in-proj and mlp-up GEMM K-loops: first iteration peeled (C=0 instead of 128 zeroing v_mov per tile; first two counted waits allow the previous tile's 16 epilogue stores in flight)
# speedup vs baseline: 1.0029x; 1.0029x over previous
.LBB0_104:
	s_ashr_i32 s17, s16, 31
	s_lshl_b64 s[4:5], s[16:17], 19
	s_add_u32 s18, s0, s4
	s_addc_u32 s19, s2, s5
	s_and_b64 s[4:5], s[6:7], exec
	s_cselect_b32 s4, s19, s25
	s_cselect_b32 s5, s18, s24
	s_ashr_i32 s15, s14, 31
	s_lshl_b64 s[20:21], s[14:15], 19
	s_add_u32 s20, s30, s20
	s_addc_u32 s21, s31, s21
	s_and_b64 s[28:29], s[6:7], exec
	s_cselect_b32 s15, s21, s27
	s_cselect_b32 s17, s20, s26
	s_add_u32 s24, s24, 0x40080
	s_addc_u32 s25, s25, 0
	s_add_u32 s50, s26, 0x100
	s_addc_u32 s51, s27, 0
	s_mov_b32 s54, -2
	s_add_u32 s26, s24, 0xfffc0080
	s_addc_u32 s27, s25, -1
	s_add_i32 s55, 0, 0x10000
	s_cmp_eq_u32 s54, 12
	s_cselect_b32 s29, s4, s27
	s_cselect_b32 s28, s5, s26
	v_add_u32_e32 v142, s55, v146
	s_cselect_b32 s27, s15, s51
	s_cselect_b32 s26, s17, s50
	s_add_i32 s57, 0, 0x14000
	ds_read_b128 v[148:151], v142
	ds_read_b128 v[152:155], v142 offset:1024
	ds_read_b128 v[156:159], v142 offset:2048
	ds_read_b128 v[160:163], v142 offset:3072
	v_add_u32_e32 v142, s57, v146
	ds_read_b128 v[164:167], v142
	ds_read_b128 v[168:171], v142 offset:1024
	ds_read_b128 v[172:175], v142 offset:2048
	ds_read_b128 v[176:179], v142 offset:3072
	v_lshl_add_u64 v[142:143], s[24:25], 0, v[138:139]
	s_add_i32 m0, s1, 0xc000
	ds_read_b128 v[188:191], v147
	ds_read_b128 v[192:195], v147 offset:1024
	ds_read_b128 v[196:199], v147 offset:2048
	ds_read_b128 v[200:203], v147 offset:3072
	ds_read_b128 v[204:207], v147 offset:4096
	ds_read_b128 v[208:211], v147 offset:5120
	ds_read_b128 v[212:215], v147 offset:6144
	ds_read_b128 v[216:219], v147 offset:7168
	global_load_lds_dwordx4 v[142:143], off
	v_lshl_add_u64 v[142:143], s[24:25], 0, v[140:141]
	s_add_i32 m0, s1, 0xe000
	s_nop 0
	global_load_lds_dwordx4 v[142:143], off
	s_waitcnt vmcnt(24)
	s_waitcnt lgkmcnt(0)
	s_barrier
	s_setprio 1
	s_waitcnt lgkmcnt(0)
	v_mfma_f32_16x16x32_bf16 v[128:131], v[148:151], v[188:191], 0
	v_mfma_f32_16x16x32_bf16 v[124:127], v[156:159], v[188:191], 0
	v_mfma_f32_16x16x32_bf16 v[112:115], v[148:151], v[196:199], 0
	v_mfma_f32_16x16x32_bf16 v[108:111], v[156:159], v[196:199], 0
	v_mfma_f32_16x16x32_bf16 v[96:99], v[148:151], v[204:207], 0
	v_mfma_f32_16x16x32_bf16 v[92:95], v[156:159], v[204:207], 0
	v_mfma_f32_16x16x32_bf16 v[80:83], v[148:151], v[212:215], 0
	v_mfma_f32_16x16x32_bf16 v[76:79], v[156:159], v[212:215], 0
	v_mfma_f32_16x16x32_bf16 v[128:131], v[152:155], v[192:195], v[128:131]
	v_mfma_f32_16x16x32_bf16 v[124:127], v[160:163], v[192:195], v[124:127]
	v_mfma_f32_16x16x32_bf16 v[112:115], v[152:155], v[200:203], v[112:115]
	v_mfma_f32_16x16x32_bf16 v[108:111], v[160:163], v[200:203], v[108:111]
	v_mfma_f32_16x16x32_bf16 v[96:99], v[152:155], v[208:211], v[96:99]
	v_mfma_f32_16x16x32_bf16 v[92:95], v[160:163], v[208:211], v[92:95]
	v_mfma_f32_16x16x32_bf16 v[80:83], v[152:155], v[216:219], v[80:83]
	v_mfma_f32_16x16x32_bf16 v[76:79], v[160:163], v[216:219], v[76:79]
	s_setprio 0
	s_setprio 1
	v_mfma_f32_16x16x32_bf16 v[120:123], v[164:167], v[188:191], 0
	v_mfma_f32_16x16x32_bf16 v[116:119], v[172:175], v[188:191], 0
	v_mfma_f32_16x16x32_bf16 v[104:107], v[164:167], v[196:199], 0
	v_mfma_f32_16x16x32_bf16 v[100:103], v[172:175], v[196:199], 0
	v_mfma_f32_16x16x32_bf16 v[88:91], v[164:167], v[204:207], 0
	v_mfma_f32_16x16x32_bf16 v[84:87], v[172:175], v[204:207], 0
	v_mfma_f32_16x16x32_bf16 v[72:75], v[164:167], v[212:215], 0
	v_mfma_f32_16x16x32_bf16 v[68:71], v[172:175], v[212:215], 0
	v_mfma_f32_16x16x32_bf16 v[120:123], v[168:171], v[192:195], v[120:123]
	v_mfma_f32_16x16x32_bf16 v[116:119], v[176:179], v[192:195], v[116:119]
	v_mfma_f32_16x16x32_bf16 v[104:107], v[168:171], v[200:203], v[104:107]
	v_mfma_f32_16x16x32_bf16 v[100:103], v[176:179], v[200:203], v[100:103]
	v_mfma_f32_16x16x32_bf16 v[88:91], v[168:171], v[208:211], v[88:91]
	v_mfma_f32_16x16x32_bf16 v[84:87], v[176:179], v[208:211], v[84:87]
	v_mfma_f32_16x16x32_bf16 v[72:75], v[168:171], v[216:219], v[72:75]
	v_mfma_f32_16x16x32_bf16 v[68:71], v[176:179], v[216:219], v[68:71]
	s_setprio 0
	s_barrier
	s_add_i32 s55, s55, s35
	v_lshl_add_u64 v[142:143], s[26:27], 0, v[180:181]
	s_mov_b32 m0, s55
	ds_read_b128 v[188:191], v147 offset:16384
	ds_read_b128 v[192:195], v147 offset:17408
	ds_read_b128 v[196:199], v147 offset:18432
	ds_read_b128 v[200:203], v147 offset:19456
	ds_read_b128 v[204:207], v147 offset:20480
	ds_read_b128 v[208:211], v147 offset:21504
	ds_read_b128 v[212:215], v147 offset:22528
	ds_read_b128 v[216:219], v147 offset:23552
	global_load_lds_dwordx4 v[142:143], off
	s_add_i32 m0, s55, 0x2000
	s_add_u32 s58, s26, 0x40000
	v_lshl_add_u64 v[220:221], s[26:27], 0, v[132:133]
	s_addc_u32 s59, s27, 0
	s_add_i32 s55, s57, s35
	global_load_lds_dwordx4 v[220:221], off
	v_lshl_add_u64 v[222:223], s[58:59], 0, v[180:181]
	s_mov_b32 m0, s55
	v_lshl_add_u64 v[224:225], s[28:29], 0, v[134:135]
	global_load_lds_dwordx4 v[222:223], off
	v_lshl_add_u64 v[222:223], s[58:59], 0, v[132:133]
	s_add_i32 m0, s55, 0x2000
	s_nop 0
	global_load_lds_dwordx4 v[222:223], off
	v_lshl_add_u64 v[222:223], s[28:29], 0, v[136:137]
	s_mov_b32 m0, s1
	s_nop 0
	global_load_lds_dwordx4 v[222:223], off
	s_mov_b32 m0, s23
	s_nop 0
	global_load_lds_dwordx4 v[224:225], off
	s_waitcnt vmcnt(24)
	s_waitcnt lgkmcnt(0)
	s_barrier
	s_setprio 1
	s_waitcnt lgkmcnt(0)
	v_mfma_f32_16x16x32_bf16 v[64:67], v[148:151], v[188:191], 0
	v_mfma_f32_16x16x32_bf16 v[60:63], v[156:159], v[188:191], 0
	v_mfma_f32_16x16x32_bf16 v[48:51], v[148:151], v[196:199], 0
	v_mfma_f32_16x16x32_bf16 v[44:47], v[156:159], v[196:199], 0
	v_mfma_f32_16x16x32_bf16 v[32:35], v[148:151], v[204:207], 0
	v_mfma_f32_16x16x32_bf16 v[28:31], v[156:159], v[204:207], 0
	v_mfma_f32_16x16x32_bf16 v[16:19], v[148:151], v[212:215], 0
	v_mfma_f32_16x16x32_bf16 v[12:15], v[156:159], v[212:215], 0
	v_mfma_f32_16x16x32_bf16 v[64:67], v[152:155], v[192:195], v[64:67]
	v_mfma_f32_16x16x32_bf16 v[60:63], v[160:163], v[192:195], v[60:63]
	v_mfma_f32_16x16x32_bf16 v[48:51], v[152:155], v[200:203], v[48:51]
	v_mfma_f32_16x16x32_bf16 v[44:47], v[160:163], v[200:203], v[44:47]
	v_mfma_f32_16x16x32_bf16 v[32:35], v[152:155], v[208:211], v[32:35]
	v_mfma_f32_16x16x32_bf16 v[28:31], v[160:163], v[208:211], v[28:31]
	v_mfma_f32_16x16x32_bf16 v[16:19], v[152:155], v[216:219], v[16:19]
	v_mfma_f32_16x16x32_bf16 v[12:15], v[160:163], v[216:219], v[12:15]
	s_setprio 0
	s_setprio 1
	v_mfma_f32_16x16x32_bf16 v[56:59], v[164:167], v[188:191], 0
	v_mfma_f32_16x16x32_bf16 v[52:55], v[172:175], v[188:191], 0
	v_mfma_f32_16x16x32_bf16 v[40:43], v[164:167], v[196:199], 0
	v_mfma_f32_16x16x32_bf16 v[36:39], v[172:175], v[196:199], 0
	v_mfma_f32_16x16x32_bf16 v[24:27], v[164:167], v[204:207], 0
	v_mfma_f32_16x16x32_bf16 v[20:23], v[172:175], v[204:207], 0
	v_mfma_f32_16x16x32_bf16 v[8:11], v[164:167], v[212:215], 0
	v_mfma_f32_16x16x32_bf16 v[4:7], v[172:175], v[212:215], 0
	v_mfma_f32_16x16x32_bf16 v[56:59], v[168:171], v[192:195], v[56:59]
	v_mfma_f32_16x16x32_bf16 v[52:55], v[176:179], v[192:195], v[52:55]
	v_mfma_f32_16x16x32_bf16 v[40:43], v[168:171], v[200:203], v[40:43]
	v_mfma_f32_16x16x32_bf16 v[36:39], v[176:179], v[200:203], v[36:39]
	v_mfma_f32_16x16x32_bf16 v[24:27], v[168:171], v[208:211], v[24:27]
	v_mfma_f32_16x16x32_bf16 v[20:23], v[176:179], v[208:211], v[20:23]
	v_mfma_f32_16x16x32_bf16 v[8:11], v[168:171], v[216:219], v[8:11]
	v_mfma_f32_16x16x32_bf16 v[4:7], v[176:179], v[216:219], v[4:7]
	s_setprio 0
	s_barrier
	s_add_i32 s55, 0, 0x18000
	s_add_i32 s57, 0, 0x1c000
	v_add_u32_e32 v160, s55, v146
	v_add_u32_e32 v176, s57, v146
	ds_read_b128 v[148:151], v160
	ds_read_b128 v[152:155], v160 offset:1024
	ds_read_b128 v[156:159], v160 offset:2048
	ds_read_b128 v[160:163], v160 offset:3072
	ds_read_b128 v[164:167], v176
	ds_read_b128 v[168:171], v176 offset:1024
	ds_read_b128 v[172:175], v176 offset:2048
	ds_read_b128 v[176:179], v176 offset:3072
	s_add_u32 s28, s28, 0x40000
	s_addc_u32 s29, s29, 0
	s_mov_b32 m0, s38
	v_lshl_add_u64 v[226:227], s[28:29], 0, v[136:137]
	ds_read_b128 v[188:191], v147 offset:32768
	ds_read_b128 v[192:195], v147 offset:33792
	ds_read_b128 v[196:199], v147 offset:34816
	ds_read_b128 v[200:203], v147 offset:35840
	ds_read_b128 v[204:207], v147 offset:36864
	ds_read_b128 v[208:211], v147 offset:37888
	ds_read_b128 v[212:215], v147 offset:38912
	ds_read_b128 v[216:219], v147 offset:39936
	global_load_lds_dwordx4 v[226:227], off
	v_lshl_add_u64 v[226:227], s[28:29], 0, v[134:135]
	s_mov_b32 m0, s39
	s_nop 0
	global_load_lds_dwordx4 v[226:227], off
	s_waitcnt vmcnt(8)
	s_waitcnt lgkmcnt(0)
	s_barrier
	s_setprio 1
	s_waitcnt lgkmcnt(0)
	v_mfma_f32_16x16x32_bf16 v[128:131], v[148:151], v[188:191], v[128:131]
	v_mfma_f32_16x16x32_bf16 v[124:127], v[156:159], v[188:191], v[124:127]
	v_mfma_f32_16x16x32_bf16 v[112:115], v[148:151], v[196:199], v[112:115]
	v_mfma_f32_16x16x32_bf16 v[108:111], v[156:159], v[196:199], v[108:111]
	v_mfma_f32_16x16x32_bf16 v[96:99], v[148:151], v[204:207], v[96:99]
	v_mfma_f32_16x16x32_bf16 v[92:95], v[156:159], v[204:207], v[92:95]
	v_mfma_f32_16x16x32_bf16 v[80:83], v[148:151], v[212:215], v[80:83]
	v_mfma_f32_16x16x32_bf16 v[76:79], v[156:159], v[212:215], v[76:79]
	v_mfma_f32_16x16x32_bf16 v[128:131], v[152:155], v[192:195], v[128:131]
	v_mfma_f32_16x16x32_bf16 v[124:127], v[160:163], v[192:195], v[124:127]
	v_mfma_f32_16x16x32_bf16 v[112:115], v[152:155], v[200:203], v[112:115]
	v_mfma_f32_16x16x32_bf16 v[108:111], v[160:163], v[200:203], v[108:111]
	v_mfma_f32_16x16x32_bf16 v[96:99], v[152:155], v[208:211], v[96:99]
	v_mfma_f32_16x16x32_bf16 v[92:95], v[160:163], v[208:211], v[92:95]
	v_mfma_f32_16x16x32_bf16 v[80:83], v[152:155], v[216:219], v[80:83]
	v_mfma_f32_16x16x32_bf16 v[76:79], v[160:163], v[216:219], v[76:79]
	s_setprio 0
	s_setprio 1
	v_mfma_f32_16x16x32_bf16 v[120:123], v[164:167], v[188:191], v[120:123]
	v_mfma_f32_16x16x32_bf16 v[116:119], v[172:175], v[188:191], v[116:119]
	v_mfma_f32_16x16x32_bf16 v[104:107], v[164:167], v[196:199], v[104:107]
	v_mfma_f32_16x16x32_bf16 v[100:103], v[172:175], v[196:199], v[100:103]
	v_mfma_f32_16x16x32_bf16 v[88:91], v[164:167], v[204:207], v[88:91]
	v_mfma_f32_16x16x32_bf16 v[84:87], v[172:175], v[204:207], v[84:87]
	v_mfma_f32_16x16x32_bf16 v[72:75], v[164:167], v[212:215], v[72:75]
	v_mfma_f32_16x16x32_bf16 v[68:71], v[172:175], v[212:215], v[68:71]
	v_mfma_f32_16x16x32_bf16 v[120:123], v[168:171], v[192:195], v[120:123]
	v_mfma_f32_16x16x32_bf16 v[116:119], v[176:179], v[192:195], v[116:119]
	v_mfma_f32_16x16x32_bf16 v[104:107], v[168:171], v[200:203], v[104:107]
	v_mfma_f32_16x16x32_bf16 v[100:103], v[176:179], v[200:203], v[100:103]
	v_mfma_f32_16x16x32_bf16 v[88:91], v[168:171], v[208:211], v[88:91]
	v_mfma_f32_16x16x32_bf16 v[84:87], v[176:179], v[208:211], v[84:87]
	v_mfma_f32_16x16x32_bf16 v[72:75], v[168:171], v[216:219], v[72:75]
	v_mfma_f32_16x16x32_bf16 v[68:71], v[176:179], v[216:219], v[68:71]
	s_setprio 0
	s_barrier
	s_add_i32 s28, s55, s35
	v_lshl_add_u64 v[142:143], v[142:143], 0, s[52:53]
	s_mov_b32 m0, s28
	ds_read_b128 v[188:191], v147 offset:49152
	ds_read_b128 v[192:195], v147 offset:50176
	ds_read_b128 v[196:199], v147 offset:51200
	ds_read_b128 v[200:203], v147 offset:52224
	ds_read_b128 v[204:207], v147 offset:53248
	ds_read_b128 v[208:211], v147 offset:54272
	ds_read_b128 v[212:215], v147 offset:55296
	ds_read_b128 v[216:219], v147 offset:56320
	global_load_lds_dwordx4 v[142:143], off
	s_add_i32 m0, s28, 0x2000
	s_add_u32 s26, s26, 0x40080
	v_lshl_add_u64 v[142:143], v[220:221], 0, s[52:53]
	s_addc_u32 s27, s27, 0
	s_add_i32 s28, s57, s35
	global_load_lds_dwordx4 v[142:143], off
	v_lshl_add_u64 v[142:143], s[26:27], 0, v[180:181]
	s_mov_b32 m0, s28
	s_nop 0
	global_load_lds_dwordx4 v[142:143], off
	v_lshl_add_u64 v[142:143], s[26:27], 0, v[132:133]
	s_add_i32 m0, s28, 0x2000
	s_nop 0
	global_load_lds_dwordx4 v[142:143], off
	v_lshl_add_u64 v[142:143], v[222:223], 0, s[52:53]
	s_mov_b32 m0, s42
	s_nop 0
	global_load_lds_dwordx4 v[142:143], off
	v_lshl_add_u64 v[142:143], v[224:225], 0, s[52:53]
	s_mov_b32 m0, s43
	s_nop 0
	global_load_lds_dwordx4 v[142:143], off
	s_waitcnt vmcnt(8)
	s_waitcnt lgkmcnt(0)
	s_barrier
	s_setprio 1
	s_waitcnt lgkmcnt(0)
	v_mfma_f32_16x16x32_bf16 v[64:67], v[148:151], v[188:191], v[64:67]
	v_mfma_f32_16x16x32_bf16 v[60:63], v[156:159], v[188:191], v[60:63]
	v_mfma_f32_16x16x32_bf16 v[48:51], v[148:151], v[196:199], v[48:51]
	v_mfma_f32_16x16x32_bf16 v[44:47], v[156:159], v[196:199], v[44:47]
	v_mfma_f32_16x16x32_bf16 v[32:35], v[148:151], v[204:207], v[32:35]
	v_mfma_f32_16x16x32_bf16 v[28:31], v[156:159], v[204:207], v[28:31]
	v_mfma_f32_16x16x32_bf16 v[16:19], v[148:151], v[212:215], v[16:19]
	v_mfma_f32_16x16x32_bf16 v[12:15], v[156:159], v[212:215], v[12:15]
	v_mfma_f32_16x16x32_bf16 v[64:67], v[152:155], v[192:195], v[64:67]
	v_mfma_f32_16x16x32_bf16 v[60:63], v[160:163], v[192:195], v[60:63]
	v_mfma_f32_16x16x32_bf16 v[48:51], v[152:155], v[200:203], v[48:51]
	v_mfma_f32_16x16x32_bf16 v[44:47], v[160:163], v[200:203], v[44:47]
	v_mfma_f32_16x16x32_bf16 v[32:35], v[152:155], v[208:211], v[32:35]
	v_mfma_f32_16x16x32_bf16 v[28:31], v[160:163], v[208:211], v[28:31]
	v_mfma_f32_16x16x32_bf16 v[16:19], v[152:155], v[216:219], v[16:19]
	v_mfma_f32_16x16x32_bf16 v[12:15], v[160:163], v[216:219], v[12:15]
	s_setprio 0
	s_setprio 1
	v_mfma_f32_16x16x32_bf16 v[56:59], v[164:167], v[188:191], v[56:59]
	v_mfma_f32_16x16x32_bf16 v[52:55], v[172:175], v[188:191], v[52:55]
	v_mfma_f32_16x16x32_bf16 v[40:43], v[164:167], v[196:199], v[40:43]
	v_mfma_f32_16x16x32_bf16 v[36:39], v[172:175], v[196:199], v[36:39]
	v_mfma_f32_16x16x32_bf16 v[24:27], v[164:167], v[204:207], v[24:27]
	v_mfma_f32_16x16x32_bf16 v[20:23], v[172:175], v[204:207], v[20:23]
	v_mfma_f32_16x16x32_bf16 v[8:11], v[164:167], v[212:215], v[8:11]
	v_mfma_f32_16x16x32_bf16 v[4:7], v[172:175], v[212:215], v[4:7]
	v_mfma_f32_16x16x32_bf16 v[56:59], v[168:171], v[192:195], v[56:59]
	v_mfma_f32_16x16x32_bf16 v[52:55], v[176:179], v[192:195], v[52:55]
	v_mfma_f32_16x16x32_bf16 v[40:43], v[168:171], v[200:203], v[40:43]
	v_mfma_f32_16x16x32_bf16 v[36:39], v[176:179], v[200:203], v[36:39]
	v_mfma_f32_16x16x32_bf16 v[24:27], v[168:171], v[208:211], v[24:27]
	v_mfma_f32_16x16x32_bf16 v[20:23], v[176:179], v[208:211], v[20:23]
	v_mfma_f32_16x16x32_bf16 v[8:11], v[168:171], v[216:219], v[8:11]
	v_mfma_f32_16x16x32_bf16 v[4:7], v[176:179], v[216:219], v[4:7]
	s_setprio 0
	s_barrier
	s_add_i32 s54, s54, 2
	s_add_u32 s24, s24, 0x100
	s_addc_u32 s25, s25, 0
	s_add_u32 s50, s50, 0x100
	s_addc_u32 s51, s51, 0
	s_cmp_gt_u32 s54, 13
	s_cbranch_scc1 .Lkexit_0

.Lkexit_0:
	s_and_b64 vcc, exec, s[12:13]
	s_cbranch_vccz .LBB0_108
	s_barrier

.LBB0_670:
	s_ashr_i32 s21, s20, 31
	s_lshl_b64 s[0:1], s[20:21], 19
	s_add_u32 s22, s8, s0
	s_addc_u32 s23, s9, s1
	s_and_b64 s[0:1], s[6:7], exec
	s_cselect_b32 s0, s23, s31
	s_cselect_b32 s1, s22, s30
	s_ashr_i32 s19, s18, 31
	s_lshl_b64 s[4:5], s[18:19], 19
	s_add_u32 s24, s40, s4
	s_addc_u32 s25, s41, s5
	s_and_b64 s[4:5], s[6:7], exec
	s_cselect_b32 s2, s25, s35
	s_cselect_b32 s4, s24, s34
	s_add_u32 s30, s30, 0x40080
	s_addc_u32 s31, s31, 0
	s_add_u32 s5, s34, 0x100
	s_addc_u32 s19, s35, 0
	s_mov_b32 s21, -2
	s_add_u32 s27, s30, 0xfffc0080
	s_addc_u32 s29, s31, -1
	s_add_i32 s33, 0, 0x10000
	s_cmp_eq_u32 s21, 12
	s_cselect_b32 s37, s0, s29
	s_cselect_b32 s36, s1, s27
	v_add_u32_e32 v144, s33, v157
	s_cselect_b32 s35, s2, s19
	s_cselect_b32 s34, s4, s5
	s_add_i32 s27, 0, 0x14000
	ds_read_b128 v[148:151], v144
	ds_read_b128 v[152:155], v144 offset:1024
	ds_read_b128 v[160:163], v144 offset:2048
	ds_read_b128 v[164:167], v144 offset:3072
	v_add_u32_e32 v144, s27, v157
	ds_read_b128 v[168:171], v144
	ds_read_b128 v[172:175], v144 offset:1024
	ds_read_b128 v[176:179], v144 offset:2048
	ds_read_b128 v[188:191], v144 offset:3072
	v_lshl_add_u64 v[144:145], s[30:31], 0, v[140:141]
	s_add_i32 m0, s43, 0xc000
	ds_read_b128 v[192:195], v158
	ds_read_b128 v[196:199], v158 offset:1024
	ds_read_b128 v[200:203], v158 offset:2048
	ds_read_b128 v[204:207], v158 offset:3072
	ds_read_b128 v[208:211], v158 offset:4096
	ds_read_b128 v[212:215], v158 offset:5120
	ds_read_b128 v[216:219], v158 offset:6144
	ds_read_b128 v[220:223], v158 offset:7168
	global_load_lds_dwordx4 v[144:145], off
	v_lshl_add_u64 v[144:145], s[30:31], 0, v[142:143]
	s_add_i32 m0, s43, 0xe000
	s_nop 0
	global_load_lds_dwordx4 v[144:145], off
	s_waitcnt vmcnt(24)
	s_waitcnt lgkmcnt(0)
	s_barrier
	s_setprio 1
	s_waitcnt lgkmcnt(0)
	v_mfma_f32_16x16x32_bf16 v[128:131], v[148:151], v[192:195], 0
	v_mfma_f32_16x16x32_bf16 v[124:127], v[160:163], v[192:195], 0
	v_mfma_f32_16x16x32_bf16 v[112:115], v[148:151], v[200:203], 0
	v_mfma_f32_16x16x32_bf16 v[108:111], v[160:163], v[200:203], 0
	v_mfma_f32_16x16x32_bf16 v[96:99], v[148:151], v[208:211], 0
	v_mfma_f32_16x16x32_bf16 v[92:95], v[160:163], v[208:211], 0
	v_mfma_f32_16x16x32_bf16 v[80:83], v[148:151], v[216:219], 0
	v_mfma_f32_16x16x32_bf16 v[76:79], v[160:163], v[216:219], 0
	v_mfma_f32_16x16x32_bf16 v[128:131], v[152:155], v[196:199], v[128:131]
	v_mfma_f32_16x16x32_bf16 v[124:127], v[164:167], v[196:199], v[124:127]
	v_mfma_f32_16x16x32_bf16 v[112:115], v[152:155], v[204:207], v[112:115]
	v_mfma_f32_16x16x32_bf16 v[108:111], v[164:167], v[204:207], v[108:111]
	v_mfma_f32_16x16x32_bf16 v[96:99], v[152:155], v[212:215], v[96:99]
	v_mfma_f32_16x16x32_bf16 v[92:95], v[164:167], v[212:215], v[92:95]
	v_mfma_f32_16x16x32_bf16 v[80:83], v[152:155], v[220:223], v[80:83]
	v_mfma_f32_16x16x32_bf16 v[76:79], v[164:167], v[220:223], v[76:79]
	s_setprio 0
	s_setprio 1
	v_mfma_f32_16x16x32_bf16 v[120:123], v[168:171], v[192:195], 0
	v_mfma_f32_16x16x32_bf16 v[116:119], v[176:179], v[192:195], 0
	v_mfma_f32_16x16x32_bf16 v[104:107], v[168:171], v[200:203], 0
	v_mfma_f32_16x16x32_bf16 v[100:103], v[176:179], v[200:203], 0
	v_mfma_f32_16x16x32_bf16 v[88:91], v[168:171], v[208:211], 0
	v_mfma_f32_16x16x32_bf16 v[84:87], v[176:179], v[208:211], 0
	v_mfma_f32_16x16x32_bf16 v[72:75], v[168:171], v[216:219], 0
	v_mfma_f32_16x16x32_bf16 v[68:71], v[176:179], v[216:219], 0
	v_mfma_f32_16x16x32_bf16 v[120:123], v[172:175], v[196:199], v[120:123]
	v_mfma_f32_16x16x32_bf16 v[116:119], v[188:191], v[196:199], v[116:119]
	v_mfma_f32_16x16x32_bf16 v[104:107], v[172:175], v[204:207], v[104:107]
	v_mfma_f32_16x16x32_bf16 v[100:103], v[188:191], v[204:207], v[100:103]
	v_mfma_f32_16x16x32_bf16 v[88:91], v[172:175], v[212:215], v[88:91]
	v_mfma_f32_16x16x32_bf16 v[84:87], v[188:191], v[212:215], v[84:87]
	v_mfma_f32_16x16x32_bf16 v[72:75], v[172:175], v[220:223], v[72:75]
	v_mfma_f32_16x16x32_bf16 v[68:71], v[188:191], v[220:223], v[68:71]
	s_setprio 0
	s_barrier
	s_add_i32 s29, s33, s42
	v_lshl_add_u64 v[144:145], s[34:35], 0, v[134:135]
	s_mov_b32 m0, s29
	ds_read_b128 v[192:195], v158 offset:16384
	ds_read_b128 v[196:199], v158 offset:17408
	ds_read_b128 v[200:203], v158 offset:18432
	ds_read_b128 v[204:207], v158 offset:19456
	ds_read_b128 v[208:211], v158 offset:20480
	ds_read_b128 v[212:215], v158 offset:21504
	ds_read_b128 v[216:219], v158 offset:22528
	ds_read_b128 v[220:223], v158 offset:23552
	global_load_lds_dwordx4 v[144:145], off
	s_add_i32 m0, s29, 0x2000
	s_add_u32 s44, s34, 0x40000
	v_lshl_add_u64 v[224:225], s[34:35], 0, v[138:139]
	s_addc_u32 s45, s35, 0
	s_add_i32 s27, s27, s42
	global_load_lds_dwordx4 v[224:225], off
	v_lshl_add_u64 v[226:227], s[44:45], 0, v[134:135]
	s_mov_b32 m0, s27
	v_lshl_add_u64 v[228:229], s[36:37], 0, v[136:137]
	global_load_lds_dwordx4 v[226:227], off
	v_lshl_add_u64 v[226:227], s[44:45], 0, v[138:139]
	s_add_i32 m0, s27, 0x2000
	s_nop 0
	global_load_lds_dwordx4 v[226:227], off
	v_lshl_add_u64 v[226:227], s[36:37], 0, v[132:133]
	s_mov_b32 m0, s43
	s_nop 0
	global_load_lds_dwordx4 v[226:227], off
	s_mov_b32 m0, s48
	s_nop 0
	global_load_lds_dwordx4 v[228:229], off
	s_waitcnt vmcnt(24)
	s_waitcnt lgkmcnt(0)
	s_barrier
	s_setprio 1
	s_waitcnt lgkmcnt(0)
	v_mfma_f32_16x16x32_bf16 v[64:67], v[148:151], v[192:195], 0
	v_mfma_f32_16x16x32_bf16 v[60:63], v[160:163], v[192:195], 0
	v_mfma_f32_16x16x32_bf16 v[48:51], v[148:151], v[200:203], 0
	v_mfma_f32_16x16x32_bf16 v[44:47], v[160:163], v[200:203], 0
	v_mfma_f32_16x16x32_bf16 v[32:35], v[148:151], v[208:211], 0
	v_mfma_f32_16x16x32_bf16 v[28:31], v[160:163], v[208:211], 0
	v_mfma_f32_16x16x32_bf16 v[16:19], v[148:151], v[216:219], 0
	v_mfma_f32_16x16x32_bf16 v[12:15], v[160:163], v[216:219], 0
	v_mfma_f32_16x16x32_bf16 v[64:67], v[152:155], v[196:199], v[64:67]
	v_mfma_f32_16x16x32_bf16 v[60:63], v[164:167], v[196:199], v[60:63]
	v_mfma_f32_16x16x32_bf16 v[48:51], v[152:155], v[204:207], v[48:51]
	v_mfma_f32_16x16x32_bf16 v[44:47], v[164:167], v[204:207], v[44:47]
	v_mfma_f32_16x16x32_bf16 v[32:35], v[152:155], v[212:215], v[32:35]
	v_mfma_f32_16x16x32_bf16 v[28:31], v[164:167], v[212:215], v[28:31]
	v_mfma_f32_16x16x32_bf16 v[16:19], v[152:155], v[220:223], v[16:19]
	v_mfma_f32_16x16x32_bf16 v[12:15], v[164:167], v[220:223], v[12:15]
	s_setprio 0
	s_setprio 1
	v_mfma_f32_16x16x32_bf16 v[56:59], v[168:171], v[192:195], 0
	v_mfma_f32_16x16x32_bf16 v[52:55], v[176:179], v[192:195], 0
	v_mfma_f32_16x16x32_bf16 v[40:43], v[168:171], v[200:203], 0
	v_mfma_f32_16x16x32_bf16 v[36:39], v[176:179], v[200:203], 0
	v_mfma_f32_16x16x32_bf16 v[24:27], v[168:171], v[208:211], 0
	v_mfma_f32_16x16x32_bf16 v[20:23], v[176:179], v[208:211], 0
	v_mfma_f32_16x16x32_bf16 v[8:11], v[168:171], v[216:219], 0
	v_mfma_f32_16x16x32_bf16 v[4:7], v[176:179], v[216:219], 0
	v_mfma_f32_16x16x32_bf16 v[56:59], v[172:175], v[196:199], v[56:59]
	v_mfma_f32_16x16x32_bf16 v[52:55], v[188:191], v[196:199], v[52:55]
	v_mfma_f32_16x16x32_bf16 v[40:43], v[172:175], v[204:207], v[40:43]
	v_mfma_f32_16x16x32_bf16 v[36:39], v[188:191], v[204:207], v[36:39]
	v_mfma_f32_16x16x32_bf16 v[24:27], v[172:175], v[212:215], v[24:27]
	v_mfma_f32_16x16x32_bf16 v[20:23], v[188:191], v[212:215], v[20:23]
	v_mfma_f32_16x16x32_bf16 v[8:11], v[172:175], v[220:223], v[8:11]
	v_mfma_f32_16x16x32_bf16 v[4:7], v[188:191], v[220:223], v[4:7]
	s_setprio 0
	s_barrier
	s_add_i32 s27, 0, 0x18000
	v_add_u32_e32 v146, s27, v157
	s_add_i32 s29, 0, 0x1c000
	ds_read_b128 v[148:151], v146
	ds_read_b128 v[152:155], v146 offset:1024
	ds_read_b128 v[160:163], v146 offset:2048
	ds_read_b128 v[164:167], v146 offset:3072
	v_add_u32_e32 v146, s29, v157
	ds_read_b128 v[168:171], v146
	ds_read_b128 v[172:175], v146 offset:1024
	ds_read_b128 v[176:179], v146 offset:2048
	ds_read_b128 v[188:191], v146 offset:3072
	s_add_u32 s36, s36, 0x40000
	s_addc_u32 s37, s37, 0
	s_mov_b32 m0, s50
	v_lshl_add_u64 v[230:231], s[36:37], 0, v[132:133]
	ds_read_b128 v[192:195], v158 offset:32768
	ds_read_b128 v[196:199], v158 offset:33792
	ds_read_b128 v[200:203], v158 offset:34816
	ds_read_b128 v[204:207], v158 offset:35840
	ds_read_b128 v[208:211], v158 offset:36864
	ds_read_b128 v[212:215], v158 offset:37888
	ds_read_b128 v[216:219], v158 offset:38912
	ds_read_b128 v[220:223], v158 offset:39936
	global_load_lds_dwordx4 v[230:231], off
	v_lshl_add_u64 v[230:231], s[36:37], 0, v[136:137]
	s_mov_b32 m0, s51
	s_nop 0
	global_load_lds_dwordx4 v[230:231], off
	s_waitcnt vmcnt(8)
	s_waitcnt lgkmcnt(0)
	s_barrier
	s_setprio 1
	s_waitcnt lgkmcnt(0)
	v_mfma_f32_16x16x32_bf16 v[128:131], v[148:151], v[192:195], v[128:131]
	v_mfma_f32_16x16x32_bf16 v[124:127], v[160:163], v[192:195], v[124:127]
	v_mfma_f32_16x16x32_bf16 v[112:115], v[148:151], v[200:203], v[112:115]
	v_mfma_f32_16x16x32_bf16 v[108:111], v[160:163], v[200:203], v[108:111]
	v_mfma_f32_16x16x32_bf16 v[96:99], v[148:151], v[208:211], v[96:99]
	v_mfma_f32_16x16x32_bf16 v[92:95], v[160:163], v[208:211], v[92:95]
	v_mfma_f32_16x16x32_bf16 v[80:83], v[148:151], v[216:219], v[80:83]
	v_mfma_f32_16x16x32_bf16 v[76:79], v[160:163], v[216:219], v[76:79]
	v_mfma_f32_16x16x32_bf16 v[128:131], v[152:155], v[196:199], v[128:131]
	v_mfma_f32_16x16x32_bf16 v[124:127], v[164:167], v[196:199], v[124:127]
	v_mfma_f32_16x16x32_bf16 v[112:115], v[152:155], v[204:207], v[112:115]
	v_mfma_f32_16x16x32_bf16 v[108:111], v[164:167], v[204:207], v[108:111]
	v_mfma_f32_16x16x32_bf16 v[96:99], v[152:155], v[212:215], v[96:99]
	v_mfma_f32_16x16x32_bf16 v[92:95], v[164:167], v[212:215], v[92:95]
	v_mfma_f32_16x16x32_bf16 v[80:83], v[152:155], v[220:223], v[80:83]
	v_mfma_f32_16x16x32_bf16 v[76:79], v[164:167], v[220:223], v[76:79]
	s_setprio 0
	s_setprio 1
	v_mfma_f32_16x16x32_bf16 v[120:123], v[168:171], v[192:195], v[120:123]
	v_mfma_f32_16x16x32_bf16 v[116:119], v[176:179], v[192:195], v[116:119]
	v_mfma_f32_16x16x32_bf16 v[104:107], v[168:171], v[200:203], v[104:107]
	v_mfma_f32_16x16x32_bf16 v[100:103], v[176:179], v[200:203], v[100:103]
	v_mfma_f32_16x16x32_bf16 v[88:91], v[168:171], v[208:211], v[88:91]
	v_mfma_f32_16x16x32_bf16 v[84:87], v[176:179], v[208:211], v[84:87]
	v_mfma_f32_16x16x32_bf16 v[72:75], v[168:171], v[216:219], v[72:75]
	v_mfma_f32_16x16x32_bf16 v[68:71], v[176:179], v[216:219], v[68:71]
	v_mfma_f32_16x16x32_bf16 v[120:123], v[172:175], v[196:199], v[120:123]
	v_mfma_f32_16x16x32_bf16 v[116:119], v[188:191], v[196:199], v[116:119]
	v_mfma_f32_16x16x32_bf16 v[104:107], v[172:175], v[204:207], v[104:107]
	v_mfma_f32_16x16x32_bf16 v[100:103], v[188:191], v[204:207], v[100:103]
	v_mfma_f32_16x16x32_bf16 v[88:91], v[172:175], v[212:215], v[88:91]
	v_mfma_f32_16x16x32_bf16 v[84:87], v[188:191], v[212:215], v[84:87]
	v_mfma_f32_16x16x32_bf16 v[72:75], v[172:175], v[220:223], v[72:75]
	v_mfma_f32_16x16x32_bf16 v[68:71], v[188:191], v[220:223], v[68:71]
	s_setprio 0
	s_barrier
	s_add_i32 s27, s27, s42
	v_lshl_add_u64 v[144:145], v[144:145], 0, s[52:53]
	s_mov_b32 m0, s27
	ds_read_b128 v[192:195], v158 offset:49152
	ds_read_b128 v[196:199], v158 offset:50176
	ds_read_b128 v[200:203], v158 offset:51200
	ds_read_b128 v[204:207], v158 offset:52224
	ds_read_b128 v[208:211], v158 offset:53248
	ds_read_b128 v[212:215], v158 offset:54272
	ds_read_b128 v[216:219], v158 offset:55296
	ds_read_b128 v[220:223], v158 offset:56320
	global_load_lds_dwordx4 v[144:145], off
	s_add_i32 m0, s27, 0x2000
	s_add_u32 s34, s34, 0x40080
	v_lshl_add_u64 v[144:145], v[224:225], 0, s[52:53]
	s_addc_u32 s35, s35, 0
	s_add_i32 s27, s29, s42
	global_load_lds_dwordx4 v[144:145], off
	v_lshl_add_u64 v[144:145], s[34:35], 0, v[134:135]
	s_mov_b32 m0, s27
	s_nop 0
	global_load_lds_dwordx4 v[144:145], off
	v_lshl_add_u64 v[144:145], s[34:35], 0, v[138:139]
	s_add_i32 m0, s27, 0x2000
	s_nop 0
	global_load_lds_dwordx4 v[144:145], off
	v_lshl_add_u64 v[144:145], v[226:227], 0, s[52:53]
	s_mov_b32 m0, s58
	s_nop 0
	global_load_lds_dwordx4 v[144:145], off
	v_lshl_add_u64 v[144:145], v[228:229], 0, s[52:53]
	s_mov_b32 m0, s59
	s_nop 0
	global_load_lds_dwordx4 v[144:145], off
	s_waitcnt vmcnt(8)
	s_waitcnt lgkmcnt(0)
	s_barrier
	s_setprio 1
	s_waitcnt lgkmcnt(0)
	v_mfma_f32_16x16x32_bf16 v[64:67], v[148:151], v[192:195], v[64:67]
	v_mfma_f32_16x16x32_bf16 v[60:63], v[160:163], v[192:195], v[60:63]
	v_mfma_f32_16x16x32_bf16 v[48:51], v[148:151], v[200:203], v[48:51]
	v_mfma_f32_16x16x32_bf16 v[44:47], v[160:163], v[200:203], v[44:47]
	v_mfma_f32_16x16x32_bf16 v[32:35], v[148:151], v[208:211], v[32:35]
	v_mfma_f32_16x16x32_bf16 v[28:31], v[160:163], v[208:211], v[28:31]
	v_mfma_f32_16x16x32_bf16 v[16:19], v[148:151], v[216:219], v[16:19]
	v_mfma_f32_16x16x32_bf16 v[12:15], v[160:163], v[216:219], v[12:15]
	v_mfma_f32_16x16x32_bf16 v[64:67], v[152:155], v[196:199], v[64:67]
	v_mfma_f32_16x16x32_bf16 v[60:63], v[164:167], v[196:199], v[60:63]
	v_mfma_f32_16x16x32_bf16 v[48:51], v[152:155], v[204:207], v[48:51]
	v_mfma_f32_16x16x32_bf16 v[44:47], v[164:167], v[204:207], v[44:47]
	v_mfma_f32_16x16x32_bf16 v[32:35], v[152:155], v[212:215], v[32:35]
	v_mfma_f32_16x16x32_bf16 v[28:31], v[164:167], v[212:215], v[28:31]
	v_mfma_f32_16x16x32_bf16 v[16:19], v[152:155], v[220:223], v[16:19]
	v_mfma_f32_16x16x32_bf16 v[12:15], v[164:167], v[220:223], v[12:15]
	s_setprio 0
	s_setprio 1
	v_mfma_f32_16x16x32_bf16 v[56:59], v[168:171], v[192:195], v[56:59]
	v_mfma_f32_16x16x32_bf16 v[52:55], v[176:179], v[192:195], v[52:55]
	v_mfma_f32_16x16x32_bf16 v[40:43], v[168:171], v[200:203], v[40:43]
	v_mfma_f32_16x16x32_bf16 v[36:39], v[176:179], v[200:203], v[36:39]
	v_mfma_f32_16x16x32_bf16 v[24:27], v[168:171], v[208:211], v[24:27]
	v_mfma_f32_16x16x32_bf16 v[20:23], v[176:179], v[208:211], v[20:23]
	v_mfma_f32_16x16x32_bf16 v[8:11], v[168:171], v[216:219], v[8:11]
	v_mfma_f32_16x16x32_bf16 v[4:7], v[176:179], v[216:219], v[4:7]
	v_mfma_f32_16x16x32_bf16 v[56:59], v[172:175], v[196:199], v[56:59]
	v_mfma_f32_16x16x32_bf16 v[52:55], v[188:191], v[196:199], v[52:55]
	v_mfma_f32_16x16x32_bf16 v[40:43], v[172:175], v[204:207], v[40:43]
	v_mfma_f32_16x16x32_bf16 v[36:39], v[188:191], v[204:207], v[36:39]
	v_mfma_f32_16x16x32_bf16 v[24:27], v[172:175], v[212:215], v[24:27]
	v_mfma_f32_16x16x32_bf16 v[20:23], v[188:191], v[212:215], v[20:23]
	v_mfma_f32_16x16x32_bf16 v[8:11], v[172:175], v[220:223], v[8:11]
	v_mfma_f32_16x16x32_bf16 v[4:7], v[188:191], v[220:223], v[4:7]
	s_setprio 0
	s_barrier
	s_add_i32 s21, s21, 2
	s_add_u32 s30, s30, 0x100
	s_addc_u32 s31, s31, 0
	s_add_u32 s5, s5, 0x100
	s_addc_u32 s19, s19, 0
	s_cmp_gt_u32 s21, 13
	s_cbranch_scc1 .Lkexit_1

.Lkexit_1:
	s_and_b64 vcc, exec, s[16:17]
	s_cbranch_vccz .LBB0_674
	s_barrier
